# grid barrier: XCD leader invalidates the XCD L2 then releases its XCD (original relay); waiting workgroups only invalidate their own L1 (workgroup-scope buffer_inv)
# speedup vs baseline: 1.0513x; 1.0079x over previous
; __device__ __forceinline__ unsigned xb_ld(unsigned* p)              { return __hip_atomic_load(p, __ATOMIC_RELAXED, __HIP_MEMORY_SCOPE_AGENT); }
; #define XB_SPIN(cond, bar) do { unsigned _sp = 0; while (cond) { __builtin_amdgcn_s_sleep(1); \
;     if ((++_sp & 255u) == 0u) { if (xb_ld(&(bar)[XB_TMO])) break; if (_sp > XB_SPIN_CAP) { atomicAdd(&(bar)[XB_TMO], 1u); break; } } } } while (0)
; __device__ __forceinline__ void xcd_barrier(const XcdBarrier& b) {
;     ...
;             XB_SPIN(xb_ld(&bar[XB_XGEN(b.x)]) == gen, bar);
;             __builtin_amdgcn_fence(__ATOMIC_ACQUIRE, "agent");
;             asm volatile("s_waitcnt vmcnt(0)" ::: "memory");
.LBB0_67:
	s_or_b64 exec, exec, s[8:9]
	s_waitcnt vmcnt(0)
	buffer_inv sc0
	s_waitcnt vmcnt(0)

; __device__ __forceinline__ unsigned xb_ld(unsigned* p)              { return __hip_atomic_load(p, __ATOMIC_RELAXED, __HIP_MEMORY_SCOPE_AGENT); }
; #define XB_SPIN(cond, bar) do { unsigned _sp = 0; while (cond) { __builtin_amdgcn_s_sleep(1); \
;     if ((++_sp & 255u) == 0u) { if (xb_ld(&(bar)[XB_TMO])) break; if (_sp > XB_SPIN_CAP) { atomicAdd(&(bar)[XB_TMO], 1u); break; } } } } while (0)
; __device__ __forceinline__ void xcd_barrier(const XcdBarrier& b) {
;     ...
;             XB_SPIN(xb_ld(&bar[XB_XGEN(b.x)]) == gen, bar);
;             __builtin_amdgcn_fence(__ATOMIC_ACQUIRE, "agent");
;             asm volatile("s_waitcnt vmcnt(0)" ::: "memory");
.LBB0_507:
	s_or_b64 exec, exec, s[12:13]
	s_waitcnt vmcnt(0)
	buffer_inv sc0
	s_waitcnt vmcnt(0)

; __device__ __forceinline__ unsigned xb_ld(unsigned* p)              { return __hip_atomic_load(p, __ATOMIC_RELAXED, __HIP_MEMORY_SCOPE_AGENT); }
; #define XB_SPIN(cond, bar) do { unsigned _sp = 0; while (cond) { __builtin_amdgcn_s_sleep(1); \
;     if ((++_sp & 255u) == 0u) { if (xb_ld(&(bar)[XB_TMO])) break; if (_sp > XB_SPIN_CAP) { atomicAdd(&(bar)[XB_TMO], 1u); break; } } } } while (0)
; __device__ __forceinline__ void xcd_barrier(const XcdBarrier& b) {
;     ...
;             XB_SPIN(xb_ld(&bar[XB_XGEN(b.x)]) == gen, bar);
;             __builtin_amdgcn_fence(__ATOMIC_ACQUIRE, "agent");
;             asm volatile("s_waitcnt vmcnt(0)" ::: "memory");
.LBB0_837:
	s_or_b64 exec, exec, s[10:11]
	s_waitcnt vmcnt(0)
	buffer_inv sc0
	s_waitcnt vmcnt(0)

; __device__ __forceinline__ unsigned xb_ld(unsigned* p)              { return __hip_atomic_load(p, __ATOMIC_RELAXED, __HIP_MEMORY_SCOPE_AGENT); }
; #define XB_SPIN(cond, bar) do { unsigned _sp = 0; while (cond) { __builtin_amdgcn_s_sleep(1); \
;     if ((++_sp & 255u) == 0u) { if (xb_ld(&(bar)[XB_TMO])) break; if (_sp > XB_SPIN_CAP) { atomicAdd(&(bar)[XB_TMO], 1u); break; } } } } while (0)
; __device__ __forceinline__ void xcd_barrier(const XcdBarrier& b) {
;     ...
;             XB_SPIN(xb_ld(&bar[XB_XGEN(b.x)]) == gen, bar);
;             __builtin_amdgcn_fence(__ATOMIC_ACQUIRE, "agent");
;             asm volatile("s_waitcnt vmcnt(0)" ::: "memory");
.LBB0_1089:
	s_or_b64 exec, exec, s[14:15]
	s_waitcnt vmcnt(0)
	buffer_inv sc0
	s_waitcnt vmcnt(0)
